# speedup vs baseline: 1.0385x; 1.0024x over previous
.LBB0_134:
	s_waitcnt vmcnt(15)
	v_cvt_scalef32_pk_f16_fp4 v53, v42, 1.0
	v_mov_b32_e32 v54, v1
	v_dot2c_f32_f16_e32 v54, v53, v44
	v_cvt_scalef32_pk_f16_fp4 v53, v42, 1.0 op_sel:[1,0,0]
	v_dot2c_f32_f16_e32 v54, v53, v45
	v_cvt_scalef32_pk_f16_fp4 v53, v42, 1.0 op_sel:[0,1,0]
	v_dot2c_f32_f16_e32 v54, v53, v46
	v_cvt_scalef32_pk_f16_fp4 v42, v42, 1.0 op_sel:[1,1,0]
	v_dot2c_f32_f16_e32 v54, v42, v47
	v_cvt_scalef32_pk_f16_fp4 v42, v43, 1.0
	v_dot2c_f32_f16_e32 v54, v42, v48
	v_cvt_scalef32_pk_f16_fp4 v42, v43, 1.0 op_sel:[1,0,0]
	v_dot2c_f32_f16_e32 v54, v42, v49
	v_cvt_scalef32_pk_f16_fp4 v42, v43, 1.0 op_sel:[0,1,0]
	v_dot2c_f32_f16_e32 v54, v42, v50
	v_cvt_scalef32_pk_f16_fp4 v42, v43, 1.0 op_sel:[1,1,0]
	v_dot2c_f32_f16_e32 v54, v42, v51
	v_cvt_scalef32_pk_f16_fp4 v42, v40, 1.0
	v_mov_b32_e32 v43, v1
	v_dot2c_f32_f16_e32 v43, v42, v44
	v_cvt_scalef32_pk_f16_fp4 v42, v40, 1.0 op_sel:[1,0,0]
	v_dot2c_f32_f16_e32 v43, v42, v45
	v_cvt_scalef32_pk_f16_fp4 v42, v40, 1.0 op_sel:[0,1,0]
	v_dot2c_f32_f16_e32 v43, v42, v46
	v_cvt_scalef32_pk_f16_fp4 v40, v40, 1.0 op_sel:[1,1,0]
	v_dot2c_f32_f16_e32 v43, v40, v47
	v_cvt_scalef32_pk_f16_fp4 v40, v41, 1.0
	v_dot2c_f32_f16_e32 v43, v40, v48
	v_cvt_scalef32_pk_f16_fp4 v40, v41, 1.0 op_sel:[1,0,0]
	v_dot2c_f32_f16_e32 v43, v40, v49
	v_cvt_scalef32_pk_f16_fp4 v40, v41, 1.0 op_sel:[0,1,0]
	v_dot2c_f32_f16_e32 v43, v40, v50
	v_cvt_scalef32_pk_f16_fp4 v40, v41, 1.0 op_sel:[1,1,0]
	v_dot2c_f32_f16_e32 v43, v40, v51
	v_cvt_scalef32_pk_f16_fp4 v40, v38, 1.0
	v_mov_b32_e32 v41, v1
	v_dot2c_f32_f16_e32 v41, v40, v44
	v_cvt_scalef32_pk_f16_fp4 v40, v38, 1.0 op_sel:[1,0,0]
	v_dot2c_f32_f16_e32 v41, v40, v45
	v_cvt_scalef32_pk_f16_fp4 v40, v38, 1.0 op_sel:[0,1,0]
	v_dot2c_f32_f16_e32 v41, v40, v46
	v_cvt_scalef32_pk_f16_fp4 v38, v38, 1.0 op_sel:[1,1,0]
	v_dot2c_f32_f16_e32 v41, v38, v47
	v_cvt_scalef32_pk_f16_fp4 v38, v39, 1.0
	v_dot2c_f32_f16_e32 v41, v38, v48
	v_cvt_scalef32_pk_f16_fp4 v38, v39, 1.0 op_sel:[1,0,0]
	v_dot2c_f32_f16_e32 v41, v38, v49
	v_cvt_scalef32_pk_f16_fp4 v38, v39, 1.0 op_sel:[0,1,0]
	v_dot2c_f32_f16_e32 v41, v38, v50
	v_cvt_scalef32_pk_f16_fp4 v38, v39, 1.0 op_sel:[1,1,0]
	v_dot2c_f32_f16_e32 v41, v38, v51
	v_cvt_scalef32_pk_f16_fp4 v38, v36, 1.0
	v_mov_b32_e32 v39, v1
	v_dot2c_f32_f16_e32 v39, v38, v44
	v_cvt_scalef32_pk_f16_fp4 v38, v36, 1.0 op_sel:[1,0,0]
	v_dot2c_f32_f16_e32 v39, v38, v45
	v_cvt_scalef32_pk_f16_fp4 v38, v36, 1.0 op_sel:[0,1,0]
	v_dot2c_f32_f16_e32 v39, v38, v46
	v_cvt_scalef32_pk_f16_fp4 v36, v36, 1.0 op_sel:[1,1,0]
	v_dot2c_f32_f16_e32 v39, v36, v47
	v_cvt_scalef32_pk_f16_fp4 v36, v37, 1.0
	v_dot2c_f32_f16_e32 v39, v36, v48
	v_cvt_scalef32_pk_f16_fp4 v36, v37, 1.0 op_sel:[1,0,0]
	v_dot2c_f32_f16_e32 v39, v36, v49
	v_cvt_scalef32_pk_f16_fp4 v36, v37, 1.0 op_sel:[0,1,0]
	v_dot2c_f32_f16_e32 v39, v36, v50
	v_cvt_scalef32_pk_f16_fp4 v36, v37, 1.0 op_sel:[1,1,0]
	v_dot2c_f32_f16_e32 v39, v36, v51
	v_cvt_scalef32_pk_f16_fp4 v36, v34, 1.0
	v_mov_b32_e32 v37, v1
	v_dot2c_f32_f16_e32 v37, v36, v44
	v_cvt_scalef32_pk_f16_fp4 v36, v34, 1.0 op_sel:[1,0,0]
	v_dot2c_f32_f16_e32 v37, v36, v45
	v_cvt_scalef32_pk_f16_fp4 v36, v34, 1.0 op_sel:[0,1,0]
	v_dot2c_f32_f16_e32 v37, v36, v46
	v_cvt_scalef32_pk_f16_fp4 v34, v34, 1.0 op_sel:[1,1,0]
	v_dot2c_f32_f16_e32 v37, v34, v47
	v_cvt_scalef32_pk_f16_fp4 v34, v35, 1.0
	v_dot2c_f32_f16_e32 v37, v34, v48
	v_cvt_scalef32_pk_f16_fp4 v34, v35, 1.0 op_sel:[1,0,0]
	v_dot2c_f32_f16_e32 v37, v34, v49
	v_cvt_scalef32_pk_f16_fp4 v34, v35, 1.0 op_sel:[0,1,0]
	v_dot2c_f32_f16_e32 v37, v34, v50
	v_cvt_scalef32_pk_f16_fp4 v34, v35, 1.0 op_sel:[1,1,0]
	v_dot2c_f32_f16_e32 v37, v34, v51
	v_cvt_scalef32_pk_f16_fp4 v34, v32, 1.0
	v_mov_b32_e32 v35, v1
	v_dot2c_f32_f16_e32 v35, v34, v44
	v_cvt_scalef32_pk_f16_fp4 v34, v32, 1.0 op_sel:[1,0,0]
	v_dot2c_f32_f16_e32 v35, v34, v45
	v_cvt_scalef32_pk_f16_fp4 v34, v32, 1.0 op_sel:[0,1,0]
	v_dot2c_f32_f16_e32 v35, v34, v46
	v_cvt_scalef32_pk_f16_fp4 v32, v32, 1.0 op_sel:[1,1,0]
	v_dot2c_f32_f16_e32 v35, v32, v47
	v_cvt_scalef32_pk_f16_fp4 v32, v33, 1.0
	v_dot2c_f32_f16_e32 v35, v32, v48
	v_cvt_scalef32_pk_f16_fp4 v32, v33, 1.0 op_sel:[1,0,0]
	v_dot2c_f32_f16_e32 v35, v32, v49
	v_cvt_scalef32_pk_f16_fp4 v32, v33, 1.0 op_sel:[0,1,0]
	v_dot2c_f32_f16_e32 v35, v32, v50
	v_cvt_scalef32_pk_f16_fp4 v32, v33, 1.0 op_sel:[1,1,0]
	v_dot2c_f32_f16_e32 v35, v32, v51
	v_cvt_scalef32_pk_f16_fp4 v32, v30, 1.0
	v_mov_b32_e32 v33, v1
	v_dot2c_f32_f16_e32 v33, v32, v44
	v_cvt_scalef32_pk_f16_fp4 v32, v30, 1.0 op_sel:[1,0,0]
	v_dot2c_f32_f16_e32 v33, v32, v45
	v_cvt_scalef32_pk_f16_fp4 v32, v30, 1.0 op_sel:[0,1,0]
	v_dot2c_f32_f16_e32 v33, v32, v46
	v_cvt_scalef32_pk_f16_fp4 v30, v30, 1.0 op_sel:[1,1,0]
	v_dot2c_f32_f16_e32 v33, v30, v47
	v_cvt_scalef32_pk_f16_fp4 v30, v31, 1.0
	v_dot2c_f32_f16_e32 v33, v30, v48
	v_cvt_scalef32_pk_f16_fp4 v30, v31, 1.0 op_sel:[1,0,0]
	v_dot2c_f32_f16_e32 v33, v30, v49
	v_cvt_scalef32_pk_f16_fp4 v30, v31, 1.0 op_sel:[0,1,0]
	v_dot2c_f32_f16_e32 v33, v30, v50
	v_cvt_scalef32_pk_f16_fp4 v30, v31, 1.0 op_sel:[1,1,0]
	v_dot2c_f32_f16_e32 v33, v30, v51
	v_cvt_scalef32_pk_f16_fp4 v30, v28, 1.0
	v_mov_b32_e32 v31, v1
	v_dot2c_f32_f16_e32 v31, v30, v44
	v_cvt_scalef32_pk_f16_fp4 v30, v28, 1.0 op_sel:[1,0,0]
	v_dot2c_f32_f16_e32 v31, v30, v45
	v_cvt_scalef32_pk_f16_fp4 v30, v28, 1.0 op_sel:[0,1,0]
	v_dot2c_f32_f16_e32 v31, v30, v46
	v_cvt_scalef32_pk_f16_fp4 v28, v28, 1.0 op_sel:[1,1,0]
	v_dot2c_f32_f16_e32 v31, v28, v47
	v_cvt_scalef32_pk_f16_fp4 v28, v29, 1.0
	v_dot2c_f32_f16_e32 v31, v28, v48
	v_cvt_scalef32_pk_f16_fp4 v28, v29, 1.0 op_sel:[1,0,0]
	v_dot2c_f32_f16_e32 v31, v28, v49
	v_cvt_scalef32_pk_f16_fp4 v28, v29, 1.0 op_sel:[0,1,0]
	v_dot2c_f32_f16_e32 v31, v28, v50
	v_cvt_scalef32_pk_f16_fp4 v28, v29, 1.0 op_sel:[1,1,0]
	v_dot2c_f32_f16_e32 v31, v28, v51
	v_cvt_scalef32_pk_f16_fp4 v28, v26, 1.0
	v_mov_b32_e32 v29, v1
	v_dot2c_f32_f16_e32 v29, v28, v44
	v_cvt_scalef32_pk_f16_fp4 v28, v26, 1.0 op_sel:[1,0,0]
	v_dot2c_f32_f16_e32 v29, v28, v45
	v_cvt_scalef32_pk_f16_fp4 v28, v26, 1.0 op_sel:[0,1,0]
	v_dot2c_f32_f16_e32 v29, v28, v46
	v_cvt_scalef32_pk_f16_fp4 v26, v26, 1.0 op_sel:[1,1,0]
	v_dot2c_f32_f16_e32 v29, v26, v47
	v_cvt_scalef32_pk_f16_fp4 v26, v27, 1.0
	v_dot2c_f32_f16_e32 v29, v26, v48
	v_cvt_scalef32_pk_f16_fp4 v26, v27, 1.0 op_sel:[1,0,0]
	v_dot2c_f32_f16_e32 v29, v26, v49
	v_cvt_scalef32_pk_f16_fp4 v26, v27, 1.0 op_sel:[0,1,0]
	v_dot2c_f32_f16_e32 v29, v26, v50
	v_cvt_scalef32_pk_f16_fp4 v26, v27, 1.0 op_sel:[1,1,0]
	v_dot2c_f32_f16_e32 v29, v26, v51
	v_cvt_scalef32_pk_f16_fp4 v26, v24, 1.0
	v_mov_b32_e32 v27, v1
	v_dot2c_f32_f16_e32 v27, v26, v44
	v_cvt_scalef32_pk_f16_fp4 v26, v24, 1.0 op_sel:[1,0,0]
	v_dot2c_f32_f16_e32 v27, v26, v45
	v_cvt_scalef32_pk_f16_fp4 v26, v24, 1.0 op_sel:[0,1,0]
	v_dot2c_f32_f16_e32 v27, v26, v46
	v_cvt_scalef32_pk_f16_fp4 v24, v24, 1.0 op_sel:[1,1,0]
	v_dot2c_f32_f16_e32 v27, v24, v47
	v_cvt_scalef32_pk_f16_fp4 v24, v25, 1.0
	v_dot2c_f32_f16_e32 v27, v24, v48
	v_cvt_scalef32_pk_f16_fp4 v24, v25, 1.0 op_sel:[1,0,0]
	v_dot2c_f32_f16_e32 v27, v24, v49
	v_cvt_scalef32_pk_f16_fp4 v24, v25, 1.0 op_sel:[0,1,0]
	v_dot2c_f32_f16_e32 v27, v24, v50
	v_cvt_scalef32_pk_f16_fp4 v24, v25, 1.0 op_sel:[1,1,0]
	v_dot2c_f32_f16_e32 v27, v24, v51
	v_cvt_scalef32_pk_f16_fp4 v24, v22, 1.0
	v_mov_b32_e32 v25, v1
	v_dot2c_f32_f16_e32 v25, v24, v44
	v_cvt_scalef32_pk_f16_fp4 v24, v22, 1.0 op_sel:[1,0,0]
	v_dot2c_f32_f16_e32 v25, v24, v45
	v_cvt_scalef32_pk_f16_fp4 v24, v22, 1.0 op_sel:[0,1,0]
	v_dot2c_f32_f16_e32 v25, v24, v46
	v_cvt_scalef32_pk_f16_fp4 v22, v22, 1.0 op_sel:[1,1,0]
	v_dot2c_f32_f16_e32 v25, v22, v47
	v_cvt_scalef32_pk_f16_fp4 v22, v23, 1.0
	v_dot2c_f32_f16_e32 v25, v22, v48
	v_cvt_scalef32_pk_f16_fp4 v22, v23, 1.0 op_sel:[1,0,0]
	v_dot2c_f32_f16_e32 v25, v22, v49
	v_cvt_scalef32_pk_f16_fp4 v22, v23, 1.0 op_sel:[0,1,0]
	v_dot2c_f32_f16_e32 v25, v22, v50
	v_cvt_scalef32_pk_f16_fp4 v22, v23, 1.0 op_sel:[1,1,0]
	v_dot2c_f32_f16_e32 v25, v22, v51
	v_cvt_scalef32_pk_f16_fp4 v22, v20, 1.0
	v_mov_b32_e32 v23, v1
	v_dot2c_f32_f16_e32 v23, v22, v44
	v_cvt_scalef32_pk_f16_fp4 v22, v20, 1.0 op_sel:[1,0,0]
	v_dot2c_f32_f16_e32 v23, v22, v45
	v_cvt_scalef32_pk_f16_fp4 v22, v20, 1.0 op_sel:[0,1,0]
	v_dot2c_f32_f16_e32 v23, v22, v46
	v_cvt_scalef32_pk_f16_fp4 v20, v20, 1.0 op_sel:[1,1,0]
	v_dot2c_f32_f16_e32 v23, v20, v47
	v_cvt_scalef32_pk_f16_fp4 v20, v21, 1.0
	v_dot2c_f32_f16_e32 v23, v20, v48
	v_cvt_scalef32_pk_f16_fp4 v20, v21, 1.0 op_sel:[1,0,0]
	v_dot2c_f32_f16_e32 v23, v20, v49
	v_cvt_scalef32_pk_f16_fp4 v20, v21, 1.0 op_sel:[0,1,0]
	v_dot2c_f32_f16_e32 v23, v20, v50
	v_cvt_scalef32_pk_f16_fp4 v20, v21, 1.0 op_sel:[1,1,0]
	v_dot2c_f32_f16_e32 v23, v20, v51
	v_cvt_scalef32_pk_f16_fp4 v20, v18, 1.0
	v_mov_b32_e32 v21, v1
	v_dot2c_f32_f16_e32 v21, v20, v44
	v_cvt_scalef32_pk_f16_fp4 v20, v18, 1.0 op_sel:[1,0,0]
	v_dot2c_f32_f16_e32 v21, v20, v45
	v_cvt_scalef32_pk_f16_fp4 v20, v18, 1.0 op_sel:[0,1,0]
	v_dot2c_f32_f16_e32 v21, v20, v46
	v_cvt_scalef32_pk_f16_fp4 v18, v18, 1.0 op_sel:[1,1,0]
	v_dot2c_f32_f16_e32 v21, v18, v47
	v_cvt_scalef32_pk_f16_fp4 v18, v19, 1.0
	v_dot2c_f32_f16_e32 v21, v18, v48
	v_cvt_scalef32_pk_f16_fp4 v18, v19, 1.0 op_sel:[1,0,0]
	v_dot2c_f32_f16_e32 v21, v18, v49
	v_cvt_scalef32_pk_f16_fp4 v18, v19, 1.0 op_sel:[0,1,0]
	v_dot2c_f32_f16_e32 v21, v18, v50
	v_cvt_scalef32_pk_f16_fp4 v18, v19, 1.0 op_sel:[1,1,0]
	v_dot2c_f32_f16_e32 v21, v18, v51
	v_cvt_scalef32_pk_f16_fp4 v18, v16, 1.0
	v_mov_b32_e32 v19, v1
	v_dot2c_f32_f16_e32 v19, v18, v44
	v_cvt_scalef32_pk_f16_fp4 v18, v16, 1.0 op_sel:[1,0,0]
	v_dot2c_f32_f16_e32 v19, v18, v45
	v_cvt_scalef32_pk_f16_fp4 v18, v16, 1.0 op_sel:[0,1,0]
	v_dot2c_f32_f16_e32 v19, v18, v46
	v_cvt_scalef32_pk_f16_fp4 v16, v16, 1.0 op_sel:[1,1,0]
	v_dot2c_f32_f16_e32 v19, v16, v47
	v_cvt_scalef32_pk_f16_fp4 v16, v17, 1.0
	v_dot2c_f32_f16_e32 v19, v16, v48
	v_cvt_scalef32_pk_f16_fp4 v16, v17, 1.0 op_sel:[1,0,0]
; DEVI float geluf_(float x) { return 0.5f * x * (1.f + erff(x * 0.70710678118654752f)); }
	v_dot2c_f32_f16_e32 v19, v16, v49
	v_cvt_scalef32_pk_f16_fp4 v16, v17, 1.0 op_sel:[0,1,0]
	v_dot2c_f32_f16_e32 v19, v16, v50
	v_cvt_scalef32_pk_f16_fp4 v16, v17, 1.0 op_sel:[1,1,0]
	v_dot2c_f32_f16_e32 v19, v16, v51
	v_cvt_scalef32_pk_f16_fp4 v16, v14, 1.0
	v_mov_b32_e32 v17, v1
	v_dot2c_f32_f16_e32 v17, v16, v44
	v_cvt_scalef32_pk_f16_fp4 v16, v14, 1.0 op_sel:[1,0,0]
	v_dot2c_f32_f16_e32 v17, v16, v45
	v_cvt_scalef32_pk_f16_fp4 v16, v14, 1.0 op_sel:[0,1,0]
	s_lshl_b32 s2, s22, 9
	v_dot2c_f32_f16_e32 v17, v16, v46
	v_cvt_scalef32_pk_f16_fp4 v14, v14, 1.0 op_sel:[1,1,0]
	buffer_load_dwordx2 v[112:113], v142, s[52:55], s2 offen
	v_dot2c_f32_f16_e32 v17, v14, v47
	global_load_dword v14, v[10:11], off
	v_cvt_scalef32_pk_f16_fp4 v16, v15, 1.0
	v_dot2c_f32_f16_e32 v17, v16, v48
	v_cvt_scalef32_pk_f16_fp4 v16, v15, 1.0 op_sel:[1,0,0]
	v_dot2c_f32_f16_e32 v17, v16, v49
	v_cvt_scalef32_pk_f16_fp4 v16, v15, 1.0 op_sel:[0,1,0]
	v_dot2c_f32_f16_e32 v17, v16, v50
	v_cvt_scalef32_pk_f16_fp4 v15, v15, 1.0 op_sel:[1,1,0]
	v_dot2c_f32_f16_e32 v17, v15, v51
	v_cvt_scalef32_pk_f16_fp4 v15, v12, 1.0
	v_mov_b32_e32 v16, v1
	v_dot2c_f32_f16_e32 v16, v15, v44
	v_cvt_scalef32_pk_f16_fp4 v15, v12, 1.0 op_sel:[1,0,0]
	v_dot2c_f32_f16_e32 v16, v15, v45
	v_cvt_scalef32_pk_f16_fp4 v15, v12, 1.0 op_sel:[0,1,0]
	v_dot2c_f32_f16_e32 v16, v15, v46
	v_cvt_scalef32_pk_f16_fp4 v12, v12, 1.0 op_sel:[1,1,0]
	v_dot2c_f32_f16_e32 v16, v12, v47
	v_cvt_scalef32_pk_f16_fp4 v12, v13, 1.0
	v_dot2c_f32_f16_e32 v16, v12, v48
	v_cvt_scalef32_pk_f16_fp4 v12, v13, 1.0 op_sel:[1,0,0]
	v_dot2c_f32_f16_e32 v16, v12, v49
	v_cvt_scalef32_pk_f16_fp4 v12, v13, 1.0 op_sel:[0,1,0]
	v_dot2c_f32_f16_e32 v16, v12, v50
	v_cvt_scalef32_pk_f16_fp4 v12, v13, 1.0 op_sel:[1,1,0]
	v_dot2c_f32_f16_e32 v16, v12, v51
	v_permlane32_swap_b32_e32 v54, v29
	v_permlane32_swap_b32_e32 v41, v25
	v_permlane32_swap_b32_e32 v37, v21
	v_permlane32_swap_b32_e32 v33, v17
	v_add_f32_e32 v12, v54, v29
	v_permlane32_swap_b32_e32 v43, v27
	v_add_f32_e32 v15, v41, v25
	v_permlane32_swap_b32_e32 v39, v23
	v_add_f32_e32 v20, v37, v21
	v_permlane32_swap_b32_e32 v35, v19
	v_add_f32_e32 v17, v33, v17
	v_permlane32_swap_b32_e32 v31, v16
	v_add_f32_e32 v13, v43, v27
	v_add_f32_e32 v18, v39, v23
	v_add_f32_e32 v19, v35, v19
	v_add_f32_e32 v16, v31, v16
	v_permlane16_swap_b32_e32 v12, v20
	v_permlane16_swap_b32_e32 v15, v17
	v_add_f32_e32 v12, v12, v20
	v_permlane16_swap_b32_e32 v13, v19
	v_add_f32_e32 v15, v15, v17
	v_permlane16_swap_b32_e32 v18, v16
	v_add_f32_e32 v13, v13, v19
	v_add_f32_e32 v16, v18, v16
	v_add_f32_dpp v12, v12, v12 row_ror:8 row_mask:0xf bank_mask:0xf bound_ctrl:1
	v_add_f32_dpp v15, v15, v15 row_ror:8 row_mask:0xf bank_mask:0xf bound_ctrl:1
	v_cndmask_b32_e64 v12, v15, v12, s[38:39]
	v_add_f32_dpp v13, v13, v13 row_ror:8 row_mask:0xf bank_mask:0xf bound_ctrl:1
	v_add_f32_dpp v15, v16, v16 row_ror:8 row_mask:0xf bank_mask:0xf bound_ctrl:1
	v_cndmask_b32_e64 v13, v15, v13, s[38:39]
	v_cndmask_b32_e64 v15, v12, v13, s[40:41]
	ds_bpermute_b32 v15, v144, v15
	v_cndmask_b32_e64 v12, v13, v12, s[40:41]
	s_waitcnt lgkmcnt(0)
	v_add_f32_e32 v12, v12, v15
	s_nop 1
	v_add_f32_dpp v12, v12, v12 quad_perm:[2,3,0,1] row_mask:0xf bank_mask:0xf bound_ctrl:1
	s_nop 1
	v_add_f32_dpp v12, v12, v12 quad_perm:[1,0,3,2] row_mask:0xf bank_mask:0xf bound_ctrl:1
	v_mul_f32_e32 v12, 0x3caaaaab, v12
	v_mul_f32_e32 v13, 0x3f3504f3, v12
	v_cmp_nlt_f32_e64 s[2:3], |v13|, 1.0
	s_and_saveexec_b64 s[22:23], s[2:3]
	s_xor_b64 s[2:3], exec, s[22:23]
	s_cbranch_execz .LBB0_137
	v_fma_f32 v15, |v13|, s29, v223
	v_fma_f32 v15, |v13|, v15, s20
	v_fma_f32 v15, |v13|, v15, s21
	v_fma_f32 v15, |v13|, v15, s28
	v_fma_f32 v15, |v13|, v15, s33
	v_fma_f32 v15, |v13|, v15, s30
	v_fma_f32 v15, |v13|, v15, |v13|
	v_mul_f32_e32 v16, 0xbfb8aa3b, v15
	v_fma_f32 v17, v15, s31, -v16
	v_rndne_f32_e32 v18, v16
	v_fmac_f32_e32 v17, 0xb2a5705f, v15
	v_sub_f32_e32 v16, v16, v18
	v_add_f32_e32 v16, v16, v17
	v_cvt_i32_f32_e32 v17, v18
	v_exp_f32_e32 v16, v16
	v_cmp_nlt_f32_e32 vcc, s96, v15
	v_ldexp_f32 v16, v16, v17
	s_nop 0
	v_cndmask_b32_e32 v16, 0, v16, vcc
	v_cmp_ngt_f32_e32 vcc, s97, v15
	s_nop 1
	v_cndmask_b32_e32 v15, v224, v16, vcc
	v_sub_f32_e32 v15, 1.0, v15
	s_andn2_saveexec_b64 s[2:3], s[2:3]
	s_cbranch_execnz .LBB0_138
